# one static s_setprio 1 for waves 0-3 at kernel start (no per-segment flips)
# speedup vs baseline: 1.0068x; 1.0068x over previous
; __device__ __forceinline__ int tid_of(int wave_id) { int t = wave_id * 64 + lane_id(); asm volatile("" : "+v"(t)); return t; }
; #define LAS __attribute__((address_space(3)))
; __device__ __forceinline__ float siluf_(float x) { return x * __builtin_amdgcn_rcpf(1.0f + __expf(-x)); }
; __device__ __forceinline__ void phase_mod(const Params& p, LAS unsigned char* lds, int vb, int nb) {
;     const int tid = tid_of(p.wave_id);
;     LAS float* sc = (LAS float*)lds;
;     LAS float* red = (LAS float*)(lds + 5 * 2048 * 4);
;     {
;         static_assert(D_MODEL == 4 * NTHREADS, "one f32x4 per thread and row");
;         f32x4 cv[5];
; #pragma unroll
;         for (int j = 0; j < 5; ++j) cv[j] = *(const f32x4*)((j < 4 ? p.c + j * D_MODEL : p.c_ctx) + 4 * tid);
; #pragma unroll
;         for (int j = 0; j < 5; ++j) { f32x4 o; o.x = siluf_(cv[j].x); o.y = siluf_(cv[j].y); o.z = siluf_(cv[j].z); o.w = siluf_(cv[j].w); *(LAS f32x4*)(sc + j * D_MODEL + 4 * tid) = o; } }
;     __syncthreads();
.LBB0_8:
	s_mov_b64 s[4:5], s[0:1]
	s_and_b32 s76, s3, 0xffffffc0
	s_cmp_lt_u32 s76, 0x100
	s_cbranch_scc0 .Lprio_done
	s_setprio 1
